# S5 task: U staged once in LDS by LDS-DMA (padded pitch), T|Q rows through a 24-quad register ring in line-pair order, inactive row blocks not loaded
# speedup vs baseline: 1.0182x; 1.0182x over previous
; #define LAS __attribute__((address_space(3)))
; DEV void s5_task(int l, int b, int g, int wave, int lane, LAS unsigned char* sm, unsigned char* ws, float* out, const float* dskip) {
;     const int lg = l * 16 + g, fr = lane & 15, fq = lane >> 4;
;     const bf16_t* TQ = (const bf16_t*)(ws + WS_S5 + (size_t)lg * S5_SIZE + S5_TQ); const bf16_t* PM = (const bf16_t*)(ws + WS_S5 + (size_t)lg * S5_SIZE + S5_P);
;     const bf16_t* U = (const bf16_t*)(ws + WS_U5) + ((size_t)g * M + (size_t)b * SEQ) * 16;
;     LAS float* Hloc = (LAS float*)sm; LAS bf16_t* Hin = (LAS bf16_t*)(sm + 32768);
;     f32x4 acc[5][4];
; #pragma unroll
;     for (int i = 0; i < 5; ++i)
; #pragma unroll
;         for (int nt = 0; nt < 4; ++nt) acc[i][nt] = (f32x4){0.f, 0.f, 0.f, 0.f};
;     __syncthreads();
; #pragma unroll 4
;     for (int s = 0; s < 16; ++s) { const int k0 = 32 * s + 8 * fq;
.Ls5s_task:
	v_lshrrev_b32_e32 v0, 4, v116
	v_lshlrev_b32_e32 v220, 4, v0
	v_lshl_add_u32 v202, v118, 10, v220
	s_lshl_b32 s1, s4, 14
	v_add_u32_e32 v202, s1, v202
	v_mul_u32_u24_e32 v198, 0x410, v118
	v_add_u32_e32 v198, v220, v198
	s_add_i32 s1, s96, 0xc000
	v_add_u32_e32 v198, s1, v198
	s_mul_i32 s21, s4, 0x2080
	s_add_i32 s21, s21, s1
	v_add_u32_e32 v203, 0x20000, v202
	v_add_u32_e32 v204, 0x40000, v202
	v_add_u32_e32 v205, 0x60000, v202
	v_add_u32_e32 v206, 0x80000, v202
	v_lshl_add_u32 v207, v118, 8, v220
	s_lshl_b32 s1, s4, 12
	v_add_u32_e32 v207, s1, v207
	v_add_u32_e32 v208, 0x8000, v207
	v_add_u32_e32 v209, 0x10000, v207
	v_add_u32_e32 v210, 0x18000, v207
	v_lshl_add_u32 v215, v118, 9, v220
	s_lshl_b32 s1, s4, 6
	s_add_i32 s1, s1, s96
	v_add_u32_e32 v215, s1, v215
	s_add_i32 s1, s96, 0x8000
	v_lshl_add_u32 v216, v116, 1, s1
	v_lshl_add_u32 v217, v116, 2, s96
	v_lshl_add_u32 v218, v118, 8, v220
	v_add_u32_e32 v218, s1, v218
	v_lshlrev_b32_e32 v220, 3, v0
	v_lshl_add_u32 v211, v118, 10, v220
	s_lshl_b32 s1, s4, 5
	v_add_u32_e32 v211, s1, v211
	v_add_u32_e32 v212, 0x4000, v211
	v_add_u32_e32 v213, 0x8000, v211
	v_add_u32_e32 v214, 0xc000, v211
	v_lshl_add_u32 v219, v118, 14, v220
	s_lshl_b32 s1, s4, 9
	v_add_u32_e32 v219, s1, v219
	s_add_i32 s8, s4, 0
	s_lshr_b32 s8, s8, 1
	s_add_i32 s9, s4, 8
	s_lshr_b32 s9, s9, 1
	s_add_i32 s10, s4, 16
	s_lshr_b32 s10, s10, 1
	s_add_i32 s11, s4, 24
	s_lshr_b32 s11, s11, 1
	s_and_b32 s1, s20, 15
	s_lshr_b32 s2, s20, 4
	s_add_i32 s3, s22, s1
	s_mul_i32 s3, s3, 0xc2400
	s_add_u32 s12, s26, s3
	s_addc_u32 s13, s27, 0
	s_add_u32 s12, s12, 0x5b02400
	s_addc_u32 s13, s13, 0
	s_add_u32 s18, s12, 0xa0000
	s_addc_u32 s19, s13, 0
	s_lshl_b32 s3, s1, 19
	s_lshl_b32 s6, s2, 16
	s_add_i32 s3, s3, s6
	s_add_u32 s14, s26, s3
	s_addc_u32 s15, s27, 0
	s_add_u32 s14, s14, 0xadd8100
	s_addc_u32 s15, s15, 0
	v_mov_b32_e32 v2, 0
	v_mov_b32_e32 v3, 0
	v_mov_b32_e32 v4, 0
	v_mov_b32_e32 v5, 0
	v_mov_b32_e32 v6, 0
	v_mov_b32_e32 v7, 0
	v_mov_b32_e32 v8, 0
	v_mov_b32_e32 v9, 0
	v_mov_b32_e32 v10, 0
	v_mov_b32_e32 v11, 0
	v_mov_b32_e32 v12, 0
	v_mov_b32_e32 v13, 0
	v_mov_b32_e32 v14, 0
	v_mov_b32_e32 v15, 0
	v_mov_b32_e32 v16, 0
	v_mov_b32_e32 v17, 0
	v_mov_b32_e32 v18, 0
	v_mov_b32_e32 v19, 0
	v_mov_b32_e32 v20, 0
	v_mov_b32_e32 v21, 0
	v_mov_b32_e32 v22, 0
	v_mov_b32_e32 v23, 0
	v_mov_b32_e32 v24, 0
	v_mov_b32_e32 v25, 0
	v_mov_b32_e32 v26, 0
	v_mov_b32_e32 v27, 0
	v_mov_b32_e32 v28, 0
	v_mov_b32_e32 v29, 0
	v_mov_b32_e32 v30, 0
	v_mov_b32_e32 v31, 0
	v_mov_b32_e32 v32, 0
	v_mov_b32_e32 v33, 0
	v_mov_b32_e32 v34, 0
	v_mov_b32_e32 v35, 0
	v_mov_b32_e32 v36, 0
	v_mov_b32_e32 v37, 0
	v_mov_b32_e32 v38, 0
	v_mov_b32_e32 v39, 0
	v_mov_b32_e32 v40, 0
	v_mov_b32_e32 v41, 0
	v_mov_b32_e32 v42, 0
	v_mov_b32_e32 v43, 0
	v_mov_b32_e32 v44, 0
	v_mov_b32_e32 v45, 0
	v_mov_b32_e32 v46, 0
	v_mov_b32_e32 v47, 0
	v_mov_b32_e32 v48, 0
	v_mov_b32_e32 v49, 0
	v_mov_b32_e32 v50, 0
	v_mov_b32_e32 v51, 0
	v_mov_b32_e32 v52, 0
	v_mov_b32_e32 v53, 0
	v_mov_b32_e32 v54, 0
	v_mov_b32_e32 v55, 0
	v_mov_b32_e32 v56, 0
	v_mov_b32_e32 v57, 0
	v_mov_b32_e32 v58, 0
	v_mov_b32_e32 v59, 0
	v_mov_b32_e32 v60, 0
	v_mov_b32_e32 v61, 0
	v_mov_b32_e32 v62, 0
	v_mov_b32_e32 v63, 0
	v_mov_b32_e32 v64, 0
	v_mov_b32_e32 v65, 0
	v_mov_b32_e32 v66, 0
	v_mov_b32_e32 v67, 0
	v_mov_b32_e32 v68, 0
	v_mov_b32_e32 v69, 0
	v_mov_b32_e32 v70, 0
	v_mov_b32_e32 v71, 0
	v_mov_b32_e32 v72, 0
	v_mov_b32_e32 v73, 0
	v_mov_b32_e32 v74, 0
	v_mov_b32_e32 v75, 0
	v_mov_b32_e32 v76, 0
	v_mov_b32_e32 v77, 0
	v_mov_b32_e32 v78, 0
	v_mov_b32_e32 v79, 0
	v_mov_b32_e32 v80, 0
	v_mov_b32_e32 v81, 0
	s_waitcnt lgkmcnt(0)
	s_barrier
	v_lshlrev_b32_e32 v200, 4, v116
	s_lshl_b32 s6, s4, 13
	v_add_u32_e32 v200, s6, v200
	v_mov_b32_e32 v201, 0
	v_lshl_add_u64 v[200:201], s[14:15], 0, v[200:201]
	s_mov_b32 s28, m0
	s_mov_b32 m0, s21
	s_nop 0
	global_load_lds_dwordx4 v[200:201], off
	v_add_co_u32_e32 v200, vcc, 0x400, v200
	s_add_i32 m0, m0, 0x410
	v_addc_co_u32_e32 v201, vcc, 0, v201, vcc
	s_nop 0
	global_load_lds_dwordx4 v[200:201], off
	v_add_co_u32_e32 v200, vcc, 0x400, v200
	s_add_i32 m0, m0, 0x410
	v_addc_co_u32_e32 v201, vcc, 0, v201, vcc
	s_nop 0
	global_load_lds_dwordx4 v[200:201], off
	v_add_co_u32_e32 v200, vcc, 0x400, v200
	s_add_i32 m0, m0, 0x410
	v_addc_co_u32_e32 v201, vcc, 0, v201, vcc
	s_nop 0
	global_load_lds_dwordx4 v[200:201], off
	v_add_co_u32_e32 v200, vcc, 0x400, v200
	s_add_i32 m0, m0, 0x410
	v_addc_co_u32_e32 v201, vcc, 0, v201, vcc
	s_nop 0
	global_load_lds_dwordx4 v[200:201], off
	v_add_co_u32_e32 v200, vcc, 0x400, v200
	s_add_i32 m0, m0, 0x410
	v_addc_co_u32_e32 v201, vcc, 0, v201, vcc
	s_nop 0
	global_load_lds_dwordx4 v[200:201], off
	v_add_co_u32_e32 v200, vcc, 0x400, v200
	s_add_i32 m0, m0, 0x410
	v_addc_co_u32_e32 v201, vcc, 0, v201, vcc
	s_nop 0
	global_load_lds_dwordx4 v[200:201], off
	v_add_co_u32_e32 v200, vcc, 0x400, v200
	s_add_i32 m0, m0, 0x410
	v_addc_co_u32_e32 v201, vcc, 0, v201, vcc
	s_nop 0
	global_load_lds_dwordx4 v[200:201], off
	s_mov_b32 m0, s28
	global_load_dwordx4 v[82:85], v202, s[12:13]
	global_load_dwordx4 v[86:89], v202, s[12:13] offset:64
	global_load_dwordx4 v[90:93], v203, s[12:13]
	global_load_dwordx4 v[94:97], v203, s[12:13] offset:64
	global_load_dwordx4 v[98:101], v204, s[12:13]
	global_load_dwordx4 v[102:105], v204, s[12:13] offset:64
	global_load_dwordx4 v[106:109], v205, s[12:13]
	global_load_dwordx4 v[110:113], v205, s[12:13] offset:64
	global_load_dwordx4 v[122:125], v206, s[12:13]
	global_load_dwordx4 v[126:129], v206, s[12:13] offset:64
	global_load_dwordx4 v[130:133], v202, s[12:13] offset:128
	global_load_dwordx4 v[134:137], v202, s[12:13] offset:192
	global_load_dwordx4 v[138:141], v203, s[12:13] offset:128
	global_load_dwordx4 v[142:145], v203, s[12:13] offset:192
	global_load_dwordx4 v[146:149], v204, s[12:13] offset:128
	global_load_dwordx4 v[150:153], v204, s[12:13] offset:192
	global_load_dwordx4 v[154:157], v205, s[12:13] offset:128
	global_load_dwordx4 v[158:161], v205, s[12:13] offset:192
	global_load_dwordx4 v[162:165], v206, s[12:13] offset:128
	global_load_dwordx4 v[166:169], v206, s[12:13] offset:192
	global_load_dwordx4 v[170:173], v203, s[12:13] offset:256
	global_load_dwordx4 v[174:177], v203, s[12:13] offset:320
	global_load_dwordx4 v[178:181], v204, s[12:13] offset:256
	global_load_dwordx4 v[182:185], v204, s[12:13] offset:320
	s_waitcnt vmcnt(24)
	s_barrier
; DEV void s5_task(int l, int b, int g, int wave, int lane, LAS unsigned char* sm, unsigned char* ws, float* out, const float* dskip) {
;     ...
;     for (int s = 0; s < 16; ++s) { const int k0 = 32 * s + 8 * fq;
;         bf16x8 bfr[4];
; #pragma unroll
;         for (int nt = 0; nt < 4; ++nt) bfr[nt] = *(const bf16x8*)(U + (size_t)(nt * 16 + fr) * 512 + k0);
; #pragma unroll
;         for (int i = 0; i < 4; ++i) { const int rt = wave + 8 * i;
;             if (2 * s <= rt) { const bf16x8 a = *(const bf16x8*)(TQ + (size_t)(rt * 16 + fr) * 512 + k0);
; #pragma unroll
;                 for (int nt = 0; nt < 4; ++nt) acc[i][nt] = __builtin_amdgcn_mfma_f32_16x16x32_bf16(a, bfr[nt], acc[i][nt], 0, 0, 0); } }
;         { const bf16x8 a = *(const bf16x8*)(TQ + (size_t)((32 + wave) * 16 + fr) * 512 + k0);
; #pragma unroll
;             for (int nt = 0; nt < 4; ++nt) acc[4][nt] = __builtin_amdgcn_mfma_f32_16x16x32_bf16(a, bfr[nt], acc[4][nt], 0, 0, 0); }
;     }
	ds_read_b128 v[186:189], v198 offset:0
	ds_read_b128 v[190:193], v198 offset:16640
	ds_read_b128 v[194:197], v198 offset:33280
	ds_read_b128 v[222:225], v198 offset:49920
	ds_read_b128 v[226:229], v198 offset:64
	ds_read_b128 v[230:233], v198 offset:16704
	ds_read_b128 v[242:245], v198 offset:33344
	ds_read_b128 v[248:251], v198 offset:49984
	s_waitcnt vmcnt(15) lgkmcnt(4)
	v_mfma_f32_16x16x32_bf16 v[2:5], v[82:85], v[186:189], v[2:5]
	v_mfma_f32_16x16x32_bf16 v[6:9], v[82:85], v[190:193], v[6:9]
	v_mfma_f32_16x16x32_bf16 v[10:13], v[82:85], v[194:197], v[10:13]
	v_mfma_f32_16x16x32_bf16 v[14:17], v[82:85], v[222:225], v[14:17]
	v_mfma_f32_16x16x32_bf16 v[18:21], v[90:93], v[186:189], v[18:21]
	v_mfma_f32_16x16x32_bf16 v[22:25], v[90:93], v[190:193], v[22:25]
	v_mfma_f32_16x16x32_bf16 v[26:29], v[90:93], v[194:197], v[26:29]
	v_mfma_f32_16x16x32_bf16 v[30:33], v[90:93], v[222:225], v[30:33]
	v_mfma_f32_16x16x32_bf16 v[34:37], v[98:101], v[186:189], v[34:37]
	v_mfma_f32_16x16x32_bf16 v[38:41], v[98:101], v[190:193], v[38:41]
	v_mfma_f32_16x16x32_bf16 v[42:45], v[98:101], v[194:197], v[42:45]
	v_mfma_f32_16x16x32_bf16 v[46:49], v[98:101], v[222:225], v[46:49]
	v_mfma_f32_16x16x32_bf16 v[50:53], v[106:109], v[186:189], v[50:53]
	v_mfma_f32_16x16x32_bf16 v[54:57], v[106:109], v[190:193], v[54:57]
	v_mfma_f32_16x16x32_bf16 v[58:61], v[106:109], v[194:197], v[58:61]
	v_mfma_f32_16x16x32_bf16 v[62:65], v[106:109], v[222:225], v[62:65]
	v_mfma_f32_16x16x32_bf16 v[66:69], v[122:125], v[186:189], v[66:69]
	v_mfma_f32_16x16x32_bf16 v[70:73], v[122:125], v[190:193], v[70:73]
	v_mfma_f32_16x16x32_bf16 v[74:77], v[122:125], v[194:197], v[74:77]
	v_mfma_f32_16x16x32_bf16 v[78:81], v[122:125], v[222:225], v[78:81]
	global_load_dwordx4 v[82:85], v205, s[12:13] offset:256
	global_load_dwordx4 v[90:93], v205, s[12:13] offset:320
	global_load_dwordx4 v[98:101], v206, s[12:13] offset:256
	global_load_dwordx4 v[106:109], v206, s[12:13] offset:320
	global_load_dwordx4 v[122:125], v203, s[12:13] offset:384
	ds_read_b128 v[186:189], v198 offset:128
	ds_read_b128 v[190:193], v198 offset:16768
	ds_read_b128 v[194:197], v198 offset:33408
	ds_read_b128 v[222:225], v198 offset:50048
	s_waitcnt vmcnt(19) lgkmcnt(4)
	s_cmp_lt_u32 s8, 1
	s_cbranch_scc1 .Ls5s_sk1_0
	v_mfma_f32_16x16x32_bf16 v[2:5], v[86:89], v[226:229], v[2:5]
	v_mfma_f32_16x16x32_bf16 v[6:9], v[86:89], v[230:233], v[6:9]
	v_mfma_f32_16x16x32_bf16 v[10:13], v[86:89], v[242:245], v[10:13]
	v_mfma_f32_16x16x32_bf16 v[14:17], v[86:89], v[248:251], v[14:17]
.Ls5s_sk1_0:
	v_mfma_f32_16x16x32_bf16 v[18:21], v[94:97], v[226:229], v[18:21]
	v_mfma_f32_16x16x32_bf16 v[22:25], v[94:97], v[230:233], v[22:25]
	v_mfma_f32_16x16x32_bf16 v[26:29], v[94:97], v[242:245], v[26:29]
	v_mfma_f32_16x16x32_bf16 v[30:33], v[94:97], v[248:251], v[30:33]
	v_mfma_f32_16x16x32_bf16 v[34:37], v[102:105], v[226:229], v[34:37]
	v_mfma_f32_16x16x32_bf16 v[38:41], v[102:105], v[230:233], v[38:41]
	v_mfma_f32_16x16x32_bf16 v[42:45], v[102:105], v[242:245], v[42:45]
	v_mfma_f32_16x16x32_bf16 v[46:49], v[102:105], v[248:251], v[46:49]
	v_mfma_f32_16x16x32_bf16 v[50:53], v[110:113], v[226:229], v[50:53]
	v_mfma_f32_16x16x32_bf16 v[54:57], v[110:113], v[230:233], v[54:57]
	v_mfma_f32_16x16x32_bf16 v[58:61], v[110:113], v[242:245], v[58:61]
	v_mfma_f32_16x16x32_bf16 v[62:65], v[110:113], v[248:251], v[62:65]
	v_mfma_f32_16x16x32_bf16 v[66:69], v[126:129], v[226:229], v[66:69]
	v_mfma_f32_16x16x32_bf16 v[70:73], v[126:129], v[230:233], v[70:73]
	v_mfma_f32_16x16x32_bf16 v[74:77], v[126:129], v[242:245], v[74:77]
	v_mfma_f32_16x16x32_bf16 v[78:81], v[126:129], v[248:251], v[78:81]
	global_load_dwordx4 v[86:89], v203, s[12:13] offset:448
	global_load_dwordx4 v[94:97], v204, s[12:13] offset:384
	global_load_dwordx4 v[102:105], v204, s[12:13] offset:448
	global_load_dwordx4 v[110:113], v205, s[12:13] offset:384
	global_load_dwordx4 v[126:129], v205, s[12:13] offset:448
	ds_read_b128 v[226:229], v198 offset:192
	ds_read_b128 v[230:233], v198 offset:16832
	ds_read_b128 v[242:245], v198 offset:33472
	ds_read_b128 v[248:251], v198 offset:50112
	s_waitcnt vmcnt(15) lgkmcnt(4)
	s_cmp_lt_u32 s8, 2
	s_cbranch_scc1 .Ls5s_sk2_0
	v_mfma_f32_16x16x32_bf16 v[2:5], v[130:133], v[186:189], v[2:5]
	v_mfma_f32_16x16x32_bf16 v[6:9], v[130:133], v[190:193], v[6:9]
	v_mfma_f32_16x16x32_bf16 v[10:13], v[130:133], v[194:197], v[10:13]
	v_mfma_f32_16x16x32_bf16 v[14:17], v[130:133], v[222:225], v[14:17]
.Ls5s_sk2_0:
	v_mfma_f32_16x16x32_bf16 v[18:21], v[138:141], v[186:189], v[18:21]
	v_mfma_f32_16x16x32_bf16 v[22:25], v[138:141], v[190:193], v[22:25]
	v_mfma_f32_16x16x32_bf16 v[26:29], v[138:141], v[194:197], v[26:29]
	v_mfma_f32_16x16x32_bf16 v[30:33], v[138:141], v[222:225], v[30:33]
	v_mfma_f32_16x16x32_bf16 v[34:37], v[146:149], v[186:189], v[34:37]
	v_mfma_f32_16x16x32_bf16 v[38:41], v[146:149], v[190:193], v[38:41]
	v_mfma_f32_16x16x32_bf16 v[42:45], v[146:149], v[194:197], v[42:45]
	v_mfma_f32_16x16x32_bf16 v[46:49], v[146:149], v[222:225], v[46:49]
	v_mfma_f32_16x16x32_bf16 v[50:53], v[154:157], v[186:189], v[50:53]
	v_mfma_f32_16x16x32_bf16 v[54:57], v[154:157], v[190:193], v[54:57]
	v_mfma_f32_16x16x32_bf16 v[58:61], v[154:157], v[194:197], v[58:61]
	v_mfma_f32_16x16x32_bf16 v[62:65], v[154:157], v[222:225], v[62:65]
	v_mfma_f32_16x16x32_bf16 v[66:69], v[162:165], v[186:189], v[66:69]
	v_mfma_f32_16x16x32_bf16 v[70:73], v[162:165], v[190:193], v[70:73]
	v_mfma_f32_16x16x32_bf16 v[74:77], v[162:165], v[194:197], v[74:77]
	v_mfma_f32_16x16x32_bf16 v[78:81], v[162:165], v[222:225], v[78:81]
	global_load_dwordx4 v[130:133], v206, s[12:13] offset:384
	global_load_dwordx4 v[138:141], v206, s[12:13] offset:448
	global_load_dwordx4 v[146:149], v204, s[12:13] offset:512
	global_load_dwordx4 v[154:157], v204, s[12:13] offset:576
	global_load_dwordx4 v[162:165], v205, s[12:13] offset:512
	ds_read_b128 v[186:189], v198 offset:256
	ds_read_b128 v[190:193], v198 offset:16896
	ds_read_b128 v[194:197], v198 offset:33536
	ds_read_b128 v[222:225], v198 offset:50176
	s_waitcnt vmcnt(19) lgkmcnt(4)
	s_cmp_lt_u32 s8, 3
	s_cbranch_scc1 .Ls5s_sk3_0
	v_mfma_f32_16x16x32_bf16 v[2:5], v[134:137], v[226:229], v[2:5]
	v_mfma_f32_16x16x32_bf16 v[6:9], v[134:137], v[230:233], v[6:9]
	v_mfma_f32_16x16x32_bf16 v[10:13], v[134:137], v[242:245], v[10:13]
	v_mfma_f32_16x16x32_bf16 v[14:17], v[134:137], v[248:251], v[14:17]
; DEV void s5_task(int l, int b, int g, int wave, int lane, LAS unsigned char* sm, unsigned char* ws, float* out, const float* dskip) {
;     ...
;     for (int s = 0; s < 16; ++s) { const int k0 = 32 * s + 8 * fq;
;         bf16x8 bfr[4];
; #pragma unroll
;         for (int nt = 0; nt < 4; ++nt) bfr[nt] = *(const bf16x8*)(U + (size_t)(nt * 16 + fr) * 512 + k0);
; #pragma unroll
;         for (int i = 0; i < 4; ++i) { const int rt = wave + 8 * i;
;             if (2 * s <= rt) { const bf16x8 a = *(const bf16x8*)(TQ + (size_t)(rt * 16 + fr) * 512 + k0);
; #pragma unroll
;                 for (int nt = 0; nt < 4; ++nt) acc[i][nt] = __builtin_amdgcn_mfma_f32_16x16x32_bf16(a, bfr[nt], acc[i][nt], 0, 0, 0); } }
;         { const bf16x8 a = *(const bf16x8*)(TQ + (size_t)((32 + wave) * 16 + fr) * 512 + k0);
; #pragma unroll
;             for (int nt = 0; nt < 4; ++nt) acc[4][nt] = __builtin_amdgcn_mfma_f32_16x16x32_bf16(a, bfr[nt], acc[4][nt], 0, 0, 0); }
;     }
.Ls5s_sk3_0:
	v_mfma_f32_16x16x32_bf16 v[18:21], v[142:145], v[226:229], v[18:21]
	v_mfma_f32_16x16x32_bf16 v[22:25], v[142:145], v[230:233], v[22:25]
	v_mfma_f32_16x16x32_bf16 v[26:29], v[142:145], v[242:245], v[26:29]
	v_mfma_f32_16x16x32_bf16 v[30:33], v[142:145], v[248:251], v[30:33]
	v_mfma_f32_16x16x32_bf16 v[34:37], v[150:153], v[226:229], v[34:37]
	v_mfma_f32_16x16x32_bf16 v[38:41], v[150:153], v[230:233], v[38:41]
	v_mfma_f32_16x16x32_bf16 v[42:45], v[150:153], v[242:245], v[42:45]
	v_mfma_f32_16x16x32_bf16 v[46:49], v[150:153], v[248:251], v[46:49]
	v_mfma_f32_16x16x32_bf16 v[50:53], v[158:161], v[226:229], v[50:53]
	v_mfma_f32_16x16x32_bf16 v[54:57], v[158:161], v[230:233], v[54:57]
	v_mfma_f32_16x16x32_bf16 v[58:61], v[158:161], v[242:245], v[58:61]
	v_mfma_f32_16x16x32_bf16 v[62:65], v[158:161], v[248:251], v[62:65]
	v_mfma_f32_16x16x32_bf16 v[66:69], v[166:169], v[226:229], v[66:69]
	v_mfma_f32_16x16x32_bf16 v[70:73], v[166:169], v[230:233], v[70:73]
	v_mfma_f32_16x16x32_bf16 v[74:77], v[166:169], v[242:245], v[74:77]
	v_mfma_f32_16x16x32_bf16 v[78:81], v[166:169], v[248:251], v[78:81]
	global_load_dwordx4 v[134:137], v205, s[12:13] offset:576
	global_load_dwordx4 v[142:145], v206, s[12:13] offset:512
	global_load_dwordx4 v[150:153], v206, s[12:13] offset:576
	global_load_dwordx4 v[158:161], v204, s[12:13] offset:640
	global_load_dwordx4 v[166:169], v204, s[12:13] offset:704
	ds_read_b128 v[226:229], v198 offset:320
	ds_read_b128 v[230:233], v198 offset:16960
	ds_read_b128 v[242:245], v198 offset:33600
	ds_read_b128 v[248:251], v198 offset:50240
	s_waitcnt vmcnt(17) lgkmcnt(4)
	v_mfma_f32_16x16x32_bf16 v[18:21], v[170:173], v[186:189], v[18:21]
	v_mfma_f32_16x16x32_bf16 v[22:25], v[170:173], v[190:193], v[22:25]
	v_mfma_f32_16x16x32_bf16 v[26:29], v[170:173], v[194:197], v[26:29]
	v_mfma_f32_16x16x32_bf16 v[30:33], v[170:173], v[222:225], v[30:33]
	v_mfma_f32_16x16x32_bf16 v[34:37], v[178:181], v[186:189], v[34:37]
	v_mfma_f32_16x16x32_bf16 v[38:41], v[178:181], v[190:193], v[38:41]
	v_mfma_f32_16x16x32_bf16 v[42:45], v[178:181], v[194:197], v[42:45]
	v_mfma_f32_16x16x32_bf16 v[46:49], v[178:181], v[222:225], v[46:49]
	v_mfma_f32_16x16x32_bf16 v[50:53], v[82:85], v[186:189], v[50:53]
	v_mfma_f32_16x16x32_bf16 v[54:57], v[82:85], v[190:193], v[54:57]
	v_mfma_f32_16x16x32_bf16 v[58:61], v[82:85], v[194:197], v[58:61]
	v_mfma_f32_16x16x32_bf16 v[62:65], v[82:85], v[222:225], v[62:65]
	v_mfma_f32_16x16x32_bf16 v[66:69], v[98:101], v[186:189], v[66:69]
	v_mfma_f32_16x16x32_bf16 v[70:73], v[98:101], v[190:193], v[70:73]
	v_mfma_f32_16x16x32_bf16 v[74:77], v[98:101], v[194:197], v[74:77]
	v_mfma_f32_16x16x32_bf16 v[78:81], v[98:101], v[222:225], v[78:81]
	global_load_dwordx4 v[170:173], v205, s[12:13] offset:640
	global_load_dwordx4 v[178:181], v205, s[12:13] offset:704
	global_load_dwordx4 v[82:85], v206, s[12:13] offset:640
	global_load_dwordx4 v[98:101], v206, s[12:13] offset:704
	ds_read_b128 v[186:189], v198 offset:384
	ds_read_b128 v[190:193], v198 offset:17024
	ds_read_b128 v[194:197], v198 offset:33664
	ds_read_b128 v[222:225], v198 offset:50304
	s_waitcnt vmcnt(20) lgkmcnt(4)
	s_cmp_lt_u32 s9, 5
	s_cbranch_scc1 .Ls5s_sk5_1
	v_mfma_f32_16x16x32_bf16 v[18:21], v[174:177], v[226:229], v[18:21]
	v_mfma_f32_16x16x32_bf16 v[22:25], v[174:177], v[230:233], v[22:25]
	v_mfma_f32_16x16x32_bf16 v[26:29], v[174:177], v[242:245], v[26:29]
	v_mfma_f32_16x16x32_bf16 v[30:33], v[174:177], v[248:251], v[30:33]
.Ls5s_sk5_1:
	v_mfma_f32_16x16x32_bf16 v[34:37], v[182:185], v[226:229], v[34:37]
	v_mfma_f32_16x16x32_bf16 v[38:41], v[182:185], v[230:233], v[38:41]
	v_mfma_f32_16x16x32_bf16 v[42:45], v[182:185], v[242:245], v[42:45]
	v_mfma_f32_16x16x32_bf16 v[46:49], v[182:185], v[248:251], v[46:49]
	v_mfma_f32_16x16x32_bf16 v[50:53], v[90:93], v[226:229], v[50:53]
	v_mfma_f32_16x16x32_bf16 v[54:57], v[90:93], v[230:233], v[54:57]
	v_mfma_f32_16x16x32_bf16 v[58:61], v[90:93], v[242:245], v[58:61]
	v_mfma_f32_16x16x32_bf16 v[62:65], v[90:93], v[248:251], v[62:65]
	v_mfma_f32_16x16x32_bf16 v[66:69], v[106:109], v[226:229], v[66:69]
	v_mfma_f32_16x16x32_bf16 v[70:73], v[106:109], v[230:233], v[70:73]
	v_mfma_f32_16x16x32_bf16 v[74:77], v[106:109], v[242:245], v[74:77]
	v_mfma_f32_16x16x32_bf16 v[78:81], v[106:109], v[248:251], v[78:81]
	global_load_dwordx4 v[174:177], v205, s[12:13] offset:768
	global_load_dwordx4 v[182:185], v205, s[12:13] offset:832
	global_load_dwordx4 v[90:93], v206, s[12:13] offset:768
	global_load_dwordx4 v[106:109], v206, s[12:13] offset:832
	ds_read_b128 v[226:229], v198 offset:448
	ds_read_b128 v[230:233], v198 offset:17088
	ds_read_b128 v[242:245], v198 offset:33728
	ds_read_b128 v[248:251], v198 offset:50368
	s_waitcnt vmcnt(17) lgkmcnt(4)
	s_cmp_lt_u32 s9, 6
	s_cbranch_scc1 .Ls5s_sk6_1
	v_mfma_f32_16x16x32_bf16 v[18:21], v[122:125], v[186:189], v[18:21]
	v_mfma_f32_16x16x32_bf16 v[22:25], v[122:125], v[190:193], v[22:25]
	v_mfma_f32_16x16x32_bf16 v[26:29], v[122:125], v[194:197], v[26:29]
	v_mfma_f32_16x16x32_bf16 v[30:33], v[122:125], v[222:225], v[30:33]
; DEV void s5_task(int l, int b, int g, int wave, int lane, LAS unsigned char* sm, unsigned char* ws, float* out, const float* dskip) {
;     ...
;     for (int s = 0; s < 16; ++s) { const int k0 = 32 * s + 8 * fq;
;         bf16x8 bfr[4];
; #pragma unroll
;         for (int nt = 0; nt < 4; ++nt) bfr[nt] = *(const bf16x8*)(U + (size_t)(nt * 16 + fr) * 512 + k0);
; #pragma unroll
;         for (int i = 0; i < 4; ++i) { const int rt = wave + 8 * i;
;             if (2 * s <= rt) { const bf16x8 a = *(const bf16x8*)(TQ + (size_t)(rt * 16 + fr) * 512 + k0);
; #pragma unroll
;                 for (int nt = 0; nt < 4; ++nt) acc[i][nt] = __builtin_amdgcn_mfma_f32_16x16x32_bf16(a, bfr[nt], acc[i][nt], 0, 0, 0); } }
;         { const bf16x8 a = *(const bf16x8*)(TQ + (size_t)((32 + wave) * 16 + fr) * 512 + k0);
; #pragma unroll
;             for (int nt = 0; nt < 4; ++nt) acc[4][nt] = __builtin_amdgcn_mfma_f32_16x16x32_bf16(a, bfr[nt], acc[4][nt], 0, 0, 0); }
;     }
.Ls5s_sk6_1:
	v_mfma_f32_16x16x32_bf16 v[34:37], v[94:97], v[186:189], v[34:37]
	v_mfma_f32_16x16x32_bf16 v[38:41], v[94:97], v[190:193], v[38:41]
	v_mfma_f32_16x16x32_bf16 v[42:45], v[94:97], v[194:197], v[42:45]
	v_mfma_f32_16x16x32_bf16 v[46:49], v[94:97], v[222:225], v[46:49]
	v_mfma_f32_16x16x32_bf16 v[50:53], v[110:113], v[186:189], v[50:53]
	v_mfma_f32_16x16x32_bf16 v[54:57], v[110:113], v[190:193], v[54:57]
	v_mfma_f32_16x16x32_bf16 v[58:61], v[110:113], v[194:197], v[58:61]
	v_mfma_f32_16x16x32_bf16 v[62:65], v[110:113], v[222:225], v[62:65]
	v_mfma_f32_16x16x32_bf16 v[66:69], v[130:133], v[186:189], v[66:69]
	v_mfma_f32_16x16x32_bf16 v[70:73], v[130:133], v[190:193], v[70:73]
	v_mfma_f32_16x16x32_bf16 v[74:77], v[130:133], v[194:197], v[74:77]
	v_mfma_f32_16x16x32_bf16 v[78:81], v[130:133], v[222:225], v[78:81]
	global_load_dwordx4 v[122:125], v205, s[12:13] offset:896
	global_load_dwordx4 v[94:97], v205, s[12:13] offset:960
	global_load_dwordx4 v[110:113], v206, s[12:13] offset:896
	global_load_dwordx4 v[130:133], v206, s[12:13] offset:960
	ds_read_b128 v[186:189], v198 offset:512
	ds_read_b128 v[190:193], v198 offset:17152
	ds_read_b128 v[194:197], v198 offset:33792
	ds_read_b128 v[222:225], v198 offset:50432
	s_waitcnt vmcnt(20) lgkmcnt(4)
	s_cmp_lt_u32 s9, 7
	s_cbranch_scc1 .Ls5s_sk7_1
	v_mfma_f32_16x16x32_bf16 v[18:21], v[86:89], v[226:229], v[18:21]
	v_mfma_f32_16x16x32_bf16 v[22:25], v[86:89], v[230:233], v[22:25]
	v_mfma_f32_16x16x32_bf16 v[26:29], v[86:89], v[242:245], v[26:29]
	v_mfma_f32_16x16x32_bf16 v[30:33], v[86:89], v[248:251], v[30:33]
.Ls5s_sk7_1:
	v_mfma_f32_16x16x32_bf16 v[34:37], v[102:105], v[226:229], v[34:37]
	v_mfma_f32_16x16x32_bf16 v[38:41], v[102:105], v[230:233], v[38:41]
	v_mfma_f32_16x16x32_bf16 v[42:45], v[102:105], v[242:245], v[42:45]
	v_mfma_f32_16x16x32_bf16 v[46:49], v[102:105], v[248:251], v[46:49]
	v_mfma_f32_16x16x32_bf16 v[50:53], v[126:129], v[226:229], v[50:53]
	v_mfma_f32_16x16x32_bf16 v[54:57], v[126:129], v[230:233], v[54:57]
	v_mfma_f32_16x16x32_bf16 v[58:61], v[126:129], v[242:245], v[58:61]
	v_mfma_f32_16x16x32_bf16 v[62:65], v[126:129], v[248:251], v[62:65]
	v_mfma_f32_16x16x32_bf16 v[66:69], v[138:141], v[226:229], v[66:69]
	v_mfma_f32_16x16x32_bf16 v[70:73], v[138:141], v[230:233], v[70:73]
	v_mfma_f32_16x16x32_bf16 v[74:77], v[138:141], v[242:245], v[74:77]
	v_mfma_f32_16x16x32_bf16 v[78:81], v[138:141], v[248:251], v[78:81]
	ds_read_b128 v[226:229], v198 offset:576
	ds_read_b128 v[230:233], v198 offset:17216
	ds_read_b128 v[242:245], v198 offset:33856
	ds_read_b128 v[248:251], v198 offset:50496
	s_waitcnt vmcnt(15) lgkmcnt(4)
	v_mfma_f32_16x16x32_bf16 v[34:37], v[146:149], v[186:189], v[34:37]
	v_mfma_f32_16x16x32_bf16 v[38:41], v[146:149], v[190:193], v[38:41]
	v_mfma_f32_16x16x32_bf16 v[42:45], v[146:149], v[194:197], v[42:45]
	v_mfma_f32_16x16x32_bf16 v[46:49], v[146:149], v[222:225], v[46:49]
	v_mfma_f32_16x16x32_bf16 v[50:53], v[162:165], v[186:189], v[50:53]
	v_mfma_f32_16x16x32_bf16 v[54:57], v[162:165], v[190:193], v[54:57]
	v_mfma_f32_16x16x32_bf16 v[58:61], v[162:165], v[194:197], v[58:61]
	v_mfma_f32_16x16x32_bf16 v[62:65], v[162:165], v[222:225], v[62:65]
	v_mfma_f32_16x16x32_bf16 v[66:69], v[142:145], v[186:189], v[66:69]
	v_mfma_f32_16x16x32_bf16 v[70:73], v[142:145], v[190:193], v[70:73]
	v_mfma_f32_16x16x32_bf16 v[74:77], v[142:145], v[194:197], v[74:77]
	v_mfma_f32_16x16x32_bf16 v[78:81], v[142:145], v[222:225], v[78:81]
	ds_read_b128 v[186:189], v198 offset:640
	ds_read_b128 v[190:193], v198 offset:17280
	ds_read_b128 v[194:197], v198 offset:33920
	ds_read_b128 v[222:225], v198 offset:50560
	s_waitcnt vmcnt(14) lgkmcnt(4)
	s_cmp_lt_u32 s10, 9
	s_cbranch_scc1 .Ls5s_sk9_2
	v_mfma_f32_16x16x32_bf16 v[34:37], v[154:157], v[226:229], v[34:37]
	v_mfma_f32_16x16x32_bf16 v[38:41], v[154:157], v[230:233], v[38:41]
	v_mfma_f32_16x16x32_bf16 v[42:45], v[154:157], v[242:245], v[42:45]
	v_mfma_f32_16x16x32_bf16 v[46:49], v[154:157], v[248:251], v[46:49]
.Ls5s_sk9_2:
	v_mfma_f32_16x16x32_bf16 v[50:53], v[134:137], v[226:229], v[50:53]
	v_mfma_f32_16x16x32_bf16 v[54:57], v[134:137], v[230:233], v[54:57]
	v_mfma_f32_16x16x32_bf16 v[58:61], v[134:137], v[242:245], v[58:61]
	v_mfma_f32_16x16x32_bf16 v[62:65], v[134:137], v[248:251], v[62:65]
	v_mfma_f32_16x16x32_bf16 v[66:69], v[150:153], v[226:229], v[66:69]
	v_mfma_f32_16x16x32_bf16 v[70:73], v[150:153], v[230:233], v[70:73]
	v_mfma_f32_16x16x32_bf16 v[74:77], v[150:153], v[242:245], v[74:77]
	v_mfma_f32_16x16x32_bf16 v[78:81], v[150:153], v[248:251], v[78:81]
	ds_read_b128 v[226:229], v198 offset:704
	ds_read_b128 v[230:233], v198 offset:17344
	ds_read_b128 v[242:245], v198 offset:33984
	ds_read_b128 v[248:251], v198 offset:50624
	s_waitcnt vmcnt(9) lgkmcnt(4)
	s_cmp_lt_u32 s10, 10
	s_cbranch_scc1 .Ls5s_sk10_2
	v_mfma_f32_16x16x32_bf16 v[34:37], v[158:161], v[186:189], v[34:37]
	v_mfma_f32_16x16x32_bf16 v[38:41], v[158:161], v[190:193], v[38:41]
	v_mfma_f32_16x16x32_bf16 v[42:45], v[158:161], v[194:197], v[42:45]
	v_mfma_f32_16x16x32_bf16 v[46:49], v[158:161], v[222:225], v[46:49]
; #define LAS __attribute__((address_space(3)))
; DEV void s5_task(int l, int b, int g, int wave, int lane, LAS unsigned char* sm, unsigned char* ws, float* out, const float* dskip) {
;     ...
;     for (int s = 0; s < 16; ++s) { const int k0 = 32 * s + 8 * fq;
;         bf16x8 bfr[4];
; #pragma unroll
;         for (int nt = 0; nt < 4; ++nt) bfr[nt] = *(const bf16x8*)(U + (size_t)(nt * 16 + fr) * 512 + k0);
; #pragma unroll
;         for (int i = 0; i < 4; ++i) { const int rt = wave + 8 * i;
;             if (2 * s <= rt) { const bf16x8 a = *(const bf16x8*)(TQ + (size_t)(rt * 16 + fr) * 512 + k0);
; #pragma unroll
;                 for (int nt = 0; nt < 4; ++nt) acc[i][nt] = __builtin_amdgcn_mfma_f32_16x16x32_bf16(a, bfr[nt], acc[i][nt], 0, 0, 0); } }
;         { const bf16x8 a = *(const bf16x8*)(TQ + (size_t)((32 + wave) * 16 + fr) * 512 + k0);
; #pragma unroll
;             for (int nt = 0; nt < 4; ++nt) acc[4][nt] = __builtin_amdgcn_mfma_f32_16x16x32_bf16(a, bfr[nt], acc[4][nt], 0, 0, 0); }
;     }
; #pragma unroll
;     for (int nt = 0; nt < 4; ++nt) *(LAS f32x4*)(Hloc + (nt * 16 + fr) * 128 + 16 * wave + 4 * fq) = acc[4][nt];
;     __syncthreads();
;     if (wave == 0) { const float2 aL = ((const float2*)(ws + WS_S5 + (size_t)lg * S5_SIZE + S5_AL))[lane]; float hr = 0.f, hi = 0.f;
.Ls5s_sk10_2:
	v_mfma_f32_16x16x32_bf16 v[50:53], v[170:173], v[186:189], v[50:53]
	v_mfma_f32_16x16x32_bf16 v[54:57], v[170:173], v[190:193], v[54:57]
	v_mfma_f32_16x16x32_bf16 v[58:61], v[170:173], v[194:197], v[58:61]
	v_mfma_f32_16x16x32_bf16 v[62:65], v[170:173], v[222:225], v[62:65]
	v_mfma_f32_16x16x32_bf16 v[66:69], v[82:85], v[186:189], v[66:69]
	v_mfma_f32_16x16x32_bf16 v[70:73], v[82:85], v[190:193], v[70:73]
	v_mfma_f32_16x16x32_bf16 v[74:77], v[82:85], v[194:197], v[74:77]
	v_mfma_f32_16x16x32_bf16 v[78:81], v[82:85], v[222:225], v[78:81]
	ds_read_b128 v[186:189], v198 offset:768
	ds_read_b128 v[190:193], v198 offset:17408
	ds_read_b128 v[194:197], v198 offset:34048
	ds_read_b128 v[222:225], v198 offset:50688
	s_waitcnt vmcnt(8) lgkmcnt(4)
	s_cmp_lt_u32 s10, 11
	s_cbranch_scc1 .Ls5s_sk11_2
	v_mfma_f32_16x16x32_bf16 v[34:37], v[166:169], v[226:229], v[34:37]
	v_mfma_f32_16x16x32_bf16 v[38:41], v[166:169], v[230:233], v[38:41]
	v_mfma_f32_16x16x32_bf16 v[42:45], v[166:169], v[242:245], v[42:45]
	v_mfma_f32_16x16x32_bf16 v[46:49], v[166:169], v[248:251], v[46:49]
.Ls5s_sk11_2:
	v_mfma_f32_16x16x32_bf16 v[50:53], v[178:181], v[226:229], v[50:53]
	v_mfma_f32_16x16x32_bf16 v[54:57], v[178:181], v[230:233], v[54:57]
	v_mfma_f32_16x16x32_bf16 v[58:61], v[178:181], v[242:245], v[58:61]
	v_mfma_f32_16x16x32_bf16 v[62:65], v[178:181], v[248:251], v[62:65]
	v_mfma_f32_16x16x32_bf16 v[66:69], v[98:101], v[226:229], v[66:69]
	v_mfma_f32_16x16x32_bf16 v[70:73], v[98:101], v[230:233], v[70:73]
	v_mfma_f32_16x16x32_bf16 v[74:77], v[98:101], v[242:245], v[74:77]
	v_mfma_f32_16x16x32_bf16 v[78:81], v[98:101], v[248:251], v[78:81]
	ds_read_b128 v[226:229], v198 offset:832
	ds_read_b128 v[230:233], v198 offset:17472
	ds_read_b128 v[242:245], v198 offset:34112
	ds_read_b128 v[248:251], v198 offset:50752
	s_waitcnt vmcnt(5) lgkmcnt(4)
	v_mfma_f32_16x16x32_bf16 v[50:53], v[174:177], v[186:189], v[50:53]
	v_mfma_f32_16x16x32_bf16 v[54:57], v[174:177], v[190:193], v[54:57]
	v_mfma_f32_16x16x32_bf16 v[58:61], v[174:177], v[194:197], v[58:61]
	v_mfma_f32_16x16x32_bf16 v[62:65], v[174:177], v[222:225], v[62:65]
	v_mfma_f32_16x16x32_bf16 v[66:69], v[90:93], v[186:189], v[66:69]
	v_mfma_f32_16x16x32_bf16 v[70:73], v[90:93], v[190:193], v[70:73]
	v_mfma_f32_16x16x32_bf16 v[74:77], v[90:93], v[194:197], v[74:77]
	v_mfma_f32_16x16x32_bf16 v[78:81], v[90:93], v[222:225], v[78:81]
	ds_read_b128 v[186:189], v198 offset:896
	ds_read_b128 v[190:193], v198 offset:17536
	ds_read_b128 v[194:197], v198 offset:34176
	ds_read_b128 v[222:225], v198 offset:50816
	s_waitcnt vmcnt(4) lgkmcnt(4)
	s_cmp_lt_u32 s11, 13
	s_cbranch_scc1 .Ls5s_sk13_3
	v_mfma_f32_16x16x32_bf16 v[50:53], v[182:185], v[226:229], v[50:53]
	v_mfma_f32_16x16x32_bf16 v[54:57], v[182:185], v[230:233], v[54:57]
	v_mfma_f32_16x16x32_bf16 v[58:61], v[182:185], v[242:245], v[58:61]
	v_mfma_f32_16x16x32_bf16 v[62:65], v[182:185], v[248:251], v[62:65]
.Ls5s_sk13_3:
	v_mfma_f32_16x16x32_bf16 v[66:69], v[106:109], v[226:229], v[66:69]
	v_mfma_f32_16x16x32_bf16 v[70:73], v[106:109], v[230:233], v[70:73]
	v_mfma_f32_16x16x32_bf16 v[74:77], v[106:109], v[242:245], v[74:77]
	v_mfma_f32_16x16x32_bf16 v[78:81], v[106:109], v[248:251], v[78:81]
	ds_read_b128 v[226:229], v198 offset:960
	ds_read_b128 v[230:233], v198 offset:17600
	ds_read_b128 v[242:245], v198 offset:34240
	ds_read_b128 v[248:251], v198 offset:50880
	s_waitcnt vmcnt(1) lgkmcnt(4)
	s_cmp_lt_u32 s11, 14
	s_cbranch_scc1 .Ls5s_sk14_3
	v_mfma_f32_16x16x32_bf16 v[50:53], v[122:125], v[186:189], v[50:53]
	v_mfma_f32_16x16x32_bf16 v[54:57], v[122:125], v[190:193], v[54:57]
	v_mfma_f32_16x16x32_bf16 v[58:61], v[122:125], v[194:197], v[58:61]
	v_mfma_f32_16x16x32_bf16 v[62:65], v[122:125], v[222:225], v[62:65]
.Ls5s_sk14_3:
	v_mfma_f32_16x16x32_bf16 v[66:69], v[110:113], v[186:189], v[66:69]
	v_mfma_f32_16x16x32_bf16 v[70:73], v[110:113], v[190:193], v[70:73]
	v_mfma_f32_16x16x32_bf16 v[74:77], v[110:113], v[194:197], v[74:77]
	v_mfma_f32_16x16x32_bf16 v[78:81], v[110:113], v[222:225], v[78:81]
	s_waitcnt vmcnt(0) lgkmcnt(0)
	s_cmp_lt_u32 s11, 15
	s_cbranch_scc1 .Ls5s_sk15_3
	v_mfma_f32_16x16x32_bf16 v[50:53], v[94:97], v[226:229], v[50:53]
	v_mfma_f32_16x16x32_bf16 v[54:57], v[94:97], v[230:233], v[54:57]
	v_mfma_f32_16x16x32_bf16 v[58:61], v[94:97], v[242:245], v[58:61]
	v_mfma_f32_16x16x32_bf16 v[62:65], v[94:97], v[248:251], v[62:65]
.Ls5s_sk15_3:
	v_mfma_f32_16x16x32_bf16 v[66:69], v[130:133], v[226:229], v[66:69]
	v_mfma_f32_16x16x32_bf16 v[70:73], v[130:133], v[230:233], v[70:73]
	v_mfma_f32_16x16x32_bf16 v[74:77], v[130:133], v[242:245], v[74:77]
	v_mfma_f32_16x16x32_bf16 v[78:81], v[130:133], v[248:251], v[78:81]
	s_sub_u32 s6, s12, 0x200
	s_subb_u32 s7, s13, 0
	s_cmp_lg_u32 s4, 0
	s_cbranch_scc1 .Ls5s_noal
	v_lshlrev_b32_e32 v220, 3, v116
	global_load_dwordx2 v[226:227], v220, s[6:7]
